# v62: v61 with dead-space padding so that the GEMM main loop keeps the code placement of v59
# speedup vs baseline: 1.0029x; 1.0029x over previous
.LBB0_9:
	s_mul_i32 s3, s6, 3
	s_getpc_b64 s[0:1]
	s_add_u32 s0, s0, PROG@rel32@lo+4
	s_addc_u32 s1, s1, PROG@rel32@hi+12
	s_and_b32 s2, s3, -4
	s_add_u32 s0, s0, s2
	s_addc_u32 s1, s1, 0
	s_load_dwordx2 s[0:1], s[0:1], 0x0
	s_and_b32 s3, s3, 3
	s_lshl_b32 s3, s3, 3
	s_waitcnt lgkmcnt(0)
	s_lshr_b64 s[0:1], s[0:1], s3
	s_and_b32 s2, s0, 0xffff
	v_mov_b32_e32 v0, s2
	s_bfe_u32 s2, s0, 0x80010
	v_mov_b32_e32 v2, s2
	s_cmp_gt_u32 s6, 1
	s_cbranch_scc1 .Lsm_done
	v_readlane_b32 s0, v254, 39
	v_readlane_b32 s1, v254, 40
	s_add_u32 s0, s0, 0xc000
	s_addc_u32 s1, s1, 0
	s_cmp_eq_u32 s6, 1
	s_cbranch_scc1 .Lsm_cache
	s_getreg_b32 s2, hwreg(HW_REG_XCC_ID, 0, 4)
	s_and_b32 s2, s2, 15
	s_and_b32 s3, s66, 7
	s_cmp_eq_u32 s2, s3
	s_cbranch_scc1 .Lsm_done
	s_mov_b64 s[2:3], exec
	s_mov_b64 exec, 1
	global_atomic_add v1, v226, s[0:1]
	s_mov_b64 exec, s[2:3]
	s_branch .Lsm_done
	s_nop 0
	s_nop 0
	s_nop 0
